# hot loop heads (5 GEMM k-loops, attention tile loop, scan loop) aligned to 64 B
# speedup vs baseline: 1.0147x; 1.0147x over previous
; template <class ARowF, class KOffF>
; __device__ __forceinline__ void gemm_kloop(f32x16 (&acc)[2][2], ARowF arow, KOffF koff, const u16* __restrict__ Bt, int m0, int n0, unsigned char* smem) {
;     ...
; #pragma unroll 1
;   for (int kt = 0; kt < 16; ++kt) {
;     const int buf = kt & 1;
;     if (kt + 1 < 16) {
;       const size_t ko = koff((kt + 1) * 64); const int kb = (kt + 1) * 64;
;       ra0 = *(const u32x4*)(pa0 + ko); ra1 = *(const u32x4*)(pa1 + ko); ra2 = *(const u32x4*)(pa2 + ko); ra3 = *(const u32x4*)(pa3 + ko);
;       rb0 = *(const u32x4*)(pb0 + kb); rb1 = *(const u32x4*)(pb0 + 32 * 1024 + kb); rb2 = *(const u32x4*)(pb0 + 64 * 1024 + kb); rb3 = *(const u32x4*)(pb0 + 96 * 1024 + kb);
;     }
.LBB0_97:
	.p2align	6

; __device__ __forceinline__ void scan_chunked(const Params& p, unsigned char* smem, int bh, f32x16 (&S)[4], const int c_begin, const int c_end) {
;     ...
; #pragma unroll 1
;   for (int c = c_begin; c < c_end; ++c) {
;     if (c >= P2_SPLIT && (c & 7) == 0) {
;       const unsigned need = (c == 128) ? 1u : 8u;
;       if (tid == 0) {
;         const unsigned* f = (const unsigned*)(p.ws + OFF_BAR) + 16 + bh * 17 + (c >> 3);
;         while (__hip_atomic_load(f, __ATOMIC_RELAXED, __HIP_MEMORY_SCOPE_AGENT) < need) __builtin_amdgcn_s_sleep(2);
;         __builtin_amdgcn_fence(__ATOMIC_ACQUIRE, "agent");
;       }
;       __syncthreads();
;     }
.LBB0_314:
	s_or_b64 exec, exec, s[12:13]
	s_barrier
	.p2align	6

; __device__ __forceinline__ void attn_item(const Params& p, unsigned char* smem, int b, int h, int qb, float lam) {
;     ...
;     float rsum = 0.f;
; #pragma unroll
;     for (int mt = 0; mt < 2; ++mt)
; #pragma unroll
;       for (int r = 0; r < 16; ++r) { float pv = __builtin_amdgcn_exp2f(st[mt][r] - m_new); st[mt][r] = pv; rsum += pv; }
;     l_run = l_run * alpha + rsum; m_run = m_new;
.LBB0_331:
	v_pk_add_f32 v[82:83], v[82:83], v[84:85]
	v_pk_add_f32 v[86:87], v[86:87], v[88:89]
	v_pk_add_f32 v[90:91], v[90:91], v[92:93]
	v_pk_add_f32 v[64:65], v[64:65], v[66:67]
	v_pk_add_f32 v[68:69], v[68:69], v[70:71]
	v_pk_add_f32 v[72:73], v[72:73], v[74:75]
	v_pk_add_f32 v[76:77], v[76:77], v[78:79]
	v_add_f32_e32 v81, v81, v217
	v_pk_add_f32 v[82:83], v[82:83], v[86:87]
	v_pk_add_f32 v[90:91], v[90:91], v[94:95]
	v_pk_add_f32 v[64:65], v[64:65], v[68:69]
	v_pk_add_f32 v[72:73], v[72:73], v[76:77]
	v_pk_add_f32 v[82:83], v[82:83], v[90:91]
	v_pk_add_f32 v[64:65], v[64:65], v[72:73]
	v_pk_add_f32 v[64:65], v[64:65], v[82:83]
	v_add_f32_e32 v64, v64, v65
	v_add_f32_e32 v64, v64, v81
	s_waitcnt lgkmcnt(0)
	s_barrier
	v_fma_f32 v217, v221, v80, v64
	s_addk_i32 s55, 0x80
	s_add_i32 s54, s54, 2
	s_cmp_lt_u32 s56, s19
	s_cbranch_scc0 .LBB0_323
	.p2align	6
